# work elimination: in the last (mostly padding) column tile of the odd/even input projections, skip the B-fragment LDS reads and MFMAs of the never-stored second column half
# baseline (speedup 1.0000x reference)
; #define PG8_STAGE(bufoff, gbase, voff) do { _Pragma("unroll") for (int _i = 0; _i < 2; ++_i) \
;         __builtin_amdgcn_global_load_lds((const unsigned*)((const char*)(gbase) + (voff)[_i]), (LAS unsigned*)(lds + (bufoff) + ldsw + _i * 8192), 16, 0, 0); } while (0)
; #define PG8_LDA(dst, b, h) do { _Pragma("unroll") for (int m = 0; m < 4; ++m) _Pragma("unroll") for (int k = 0; k < 2; ++k) dst[m][k] = *(const LAS h16x8*)(lds + PG8_SA(b, h) + aoff + m * 2048 + k * 1024); } while (0)
; #define PG8_LDB(dst, b, h) do { _Pragma("unroll") for (int n = 0; n < 2; ++n) _Pragma("unroll") for (int k = 0; k < 2; ++k) dst[n][k] = *(const LAS h16x8*)(lds + PG8_SB(b, h) + boff + n * 2048 + k * 1024); } while (0)
; #define PG8_MMA(ai, bj, At, Bt) do { __builtin_amdgcn_s_setprio(1); _Pragma("unroll") for (int m = 0; m < 4; ++m) _Pragma("unroll") for (int n = 0; n < 2; ++n) _Pragma("unroll") for (int k = 0; k < 2; ++k) \
;         acc[ai][bj][m][n] = __builtin_amdgcn_mfma_f32_16x16x32_f16(Bt[n][k], At[m][k], acc[ai][bj][m][n], 0, 0, 0); __builtin_amdgcn_s_setprio(0); } while (0)
; #define PG8_WAIT_V(n) asm volatile("s_waitcnt vmcnt(" #n ")" ::: "memory")
; #define PG8_WAIT_L(n) asm volatile("s_waitcnt lgkmcnt(" #n ")" ::: "memory")
; #define PG8_BAR __builtin_amdgcn_s_barrier()
; #define PG8_SCHED __builtin_amdgcn_sched_barrier(0)
; template <class Epi>
; __device__ __forceinline__ void gemm_phase(LAS unsigned char* lds, const Gemm g, const StaticOrder& S, const Epi& E, const int wid_s) {
;     ...
;             PG8_LDB(B0, 0, 0); PG8_SCHED; PG8_LDA(At, 0, 0); PG8_STAGE(PG8_SA(1, 1), a1 + hstepA, voffA);
;             PG8_WAIT_L(8); PG8_BAR; PG8_WAIT_L(0); PG8_MMA(0, 0, At, B0); PG8_BAR; PG8_SCHED;
;             PG8_LDB(B1, 0, 1); PG8_STAGE(PG8_SB(0, 0), b2, voffB);
;             PG8_BAR; PG8_WAIT_L(0); PG8_MMA(0, 1, At, B1); PG8_BAR;
;             PG8_LDA(At, 0, 1); PG8_STAGE(PG8_SA(0, 0), a2, voffA);
;             PG8_BAR; PG8_WAIT_L(0); PG8_MMA(1, 0, At, B0); PG8_BAR; PG8_SCHED;
;             PG8_STAGE(PG8_SB(0, 1), b2 + hstepB, voffB);
;             PG8_WAIT_V(6); PG8_BAR; PG8_MMA(1, 1, At, B1); PG8_BAR;
.LBB0_146:
	s_add_u32 s12, s4, 0xfffc0080
	s_addc_u32 s13, s5, -1
	s_add_i32 s24, 0, 0x10000
	v_add_u32_e32 v152, s24, v161
	ds_read_b128 v[140:143], v152
	ds_read_b128 v[144:147], v152 offset:1024
	ds_read_b128 v[148:151], v152 offset:2048
	ds_read_b128 v[182:185], v152 offset:3072
	s_cmp_eq_u32 s23, 12
	s_cselect_b32 s15, s17, s13
	s_cselect_b32 s14, s18, s12
	s_cselect_b32 s13, s19, s22
	s_cselect_b32 s12, s20, s21
	v_lshl_add_u64 v[152:153], s[4:5], 0, v[136:137]
	s_add_i32 m0, s52, 0xc000
	ds_read_b128 v[186:189], v181
	ds_read_b128 v[190:193], v181 offset:1024
	ds_read_b128 v[194:197], v181 offset:2048
	ds_read_b128 v[198:201], v181 offset:3072
	ds_read_b128 v[202:205], v181 offset:4096
	ds_read_b128 v[206:209], v181 offset:5120
	ds_read_b128 v[210:213], v181 offset:6144
	ds_read_b128 v[228:231], v181 offset:7168
	global_load_lds_dwordx4 v[152:153], off
	v_lshl_add_u64 v[152:153], s[4:5], 0, v[138:139]
	s_add_i32 m0, s52, 0xe000
	s_nop 0
	global_load_lds_dwordx4 v[152:153], off
	s_waitcnt lgkmcnt(8)
	s_barrier
	s_waitcnt lgkmcnt(0)
	s_setprio 1
	s_waitcnt lgkmcnt(0)
	v_mfma_f32_16x16x32_f16 v[126:129], v[140:143], v[186:189], v[126:129]
	v_mfma_f32_16x16x32_f16 v[122:125], v[148:151], v[186:189], v[122:125]
	v_mfma_f32_16x16x32_f16 v[110:113], v[140:143], v[194:197], v[110:113]
	v_mfma_f32_16x16x32_f16 v[106:109], v[148:151], v[194:197], v[106:109]
	v_mfma_f32_16x16x32_f16 v[94:97], v[140:143], v[202:205], v[94:97]
	v_mfma_f32_16x16x32_f16 v[90:93], v[148:151], v[202:205], v[90:93]
	v_mfma_f32_16x16x32_f16 v[78:81], v[140:143], v[210:213], v[78:81]
	v_mfma_f32_16x16x32_f16 v[74:77], v[148:151], v[210:213], v[74:77]
	v_mfma_f32_16x16x32_f16 v[126:129], v[144:147], v[190:193], v[126:129]
	v_mfma_f32_16x16x32_f16 v[122:125], v[182:185], v[190:193], v[122:125]
	v_mfma_f32_16x16x32_f16 v[110:113], v[144:147], v[198:201], v[110:113]
	v_mfma_f32_16x16x32_f16 v[106:109], v[182:185], v[198:201], v[106:109]
	v_mfma_f32_16x16x32_f16 v[94:97], v[144:147], v[206:209], v[94:97]
	v_mfma_f32_16x16x32_f16 v[90:93], v[182:185], v[206:209], v[90:93]
	v_mfma_f32_16x16x32_f16 v[78:81], v[144:147], v[228:231], v[78:81]
	v_mfma_f32_16x16x32_f16 v[74:77], v[182:185], v[228:231], v[74:77]
	s_setprio 0
	s_barrier
	s_add_i32 s26, 0, 0x14000
	v_add_u32_e32 v152, s26, v161
	s_add_i32 s24, s24, s51
	s_cmp_eq_u32 s66, 11
	s_cbranch_scc1 .Lpad_oddin_5
	ds_read_b128 v[232:235], v152
	ds_read_b128 v[236:239], v152 offset:1024
	ds_read_b128 v[240:243], v152 offset:2048
	ds_read_b128 v[244:247], v152 offset:3072
.Lpad_oddin_5:
	v_lshl_add_u64 v[152:153], s[12:13], 0, v[0:1]
	s_mov_b32 m0, s24
	v_lshl_add_u64 v[214:215], s[12:13], 0, v[130:131]
	global_load_lds_dwordx4 v[152:153], off
	s_add_i32 m0, s24, 0x2000
	s_nop 0
	global_load_lds_dwordx4 v[214:215], off
	s_barrier
	s_waitcnt lgkmcnt(0)
	s_setprio 1
	s_waitcnt lgkmcnt(0)
	s_cmp_eq_u32 s66, 11
	s_cbranch_scc1 .Lpad_oddin_4
	v_mfma_f32_16x16x32_f16 v[118:121], v[232:235], v[186:189], v[118:121]
	v_mfma_f32_16x16x32_f16 v[114:117], v[240:243], v[186:189], v[114:117]
	v_mfma_f32_16x16x32_f16 v[102:105], v[232:235], v[194:197], v[102:105]
	v_mfma_f32_16x16x32_f16 v[98:101], v[240:243], v[194:197], v[98:101]
	v_mfma_f32_16x16x32_f16 v[86:89], v[232:235], v[202:205], v[86:89]
	v_mfma_f32_16x16x32_f16 v[82:85], v[240:243], v[202:205], v[82:85]
	v_mfma_f32_16x16x32_f16 v[70:73], v[232:235], v[210:213], v[70:73]
	v_mfma_f32_16x16x32_f16 v[66:69], v[240:243], v[210:213], v[66:69]
	v_mfma_f32_16x16x32_f16 v[118:121], v[236:239], v[190:193], v[118:121]
	v_mfma_f32_16x16x32_f16 v[114:117], v[244:247], v[190:193], v[114:117]
	v_mfma_f32_16x16x32_f16 v[102:105], v[236:239], v[198:201], v[102:105]
	v_mfma_f32_16x16x32_f16 v[98:101], v[244:247], v[198:201], v[98:101]
	v_mfma_f32_16x16x32_f16 v[86:89], v[236:239], v[206:209], v[86:89]
	v_mfma_f32_16x16x32_f16 v[82:85], v[244:247], v[206:209], v[82:85]
	v_mfma_f32_16x16x32_f16 v[70:73], v[236:239], v[228:231], v[70:73]
	v_mfma_f32_16x16x32_f16 v[66:69], v[244:247], v[228:231], v[66:69]
.Lpad_oddin_4:
	s_setprio 0
	s_mov_b32 m0, s52
	v_lshl_add_u64 v[248:249], s[14:15], 0, v[134:135]
	s_barrier
	ds_read_b128 v[186:189], v181 offset:16384
	ds_read_b128 v[190:193], v181 offset:17408
	ds_read_b128 v[194:197], v181 offset:18432
	ds_read_b128 v[198:201], v181 offset:19456
	ds_read_b128 v[202:205], v181 offset:20480
	ds_read_b128 v[206:209], v181 offset:21504
	ds_read_b128 v[210:213], v181 offset:22528
	ds_read_b128 v[228:231], v181 offset:23552
	global_load_lds_dwordx4 v[248:249], off
	v_lshl_add_u64 v[250:251], s[14:15], 0, v[132:133]
	s_mov_b32 m0, s53
	s_nop 0
	global_load_lds_dwordx4 v[250:251], off
	s_barrier
	s_waitcnt lgkmcnt(0)
	s_setprio 1
	s_waitcnt lgkmcnt(0)
	v_mfma_f32_16x16x32_f16 v[62:65], v[140:143], v[186:189], v[62:65]
	v_mfma_f32_16x16x32_f16 v[58:61], v[148:151], v[186:189], v[58:61]
	v_mfma_f32_16x16x32_f16 v[46:49], v[140:143], v[194:197], v[46:49]
	v_mfma_f32_16x16x32_f16 v[42:45], v[148:151], v[194:197], v[42:45]
	v_mfma_f32_16x16x32_f16 v[30:33], v[140:143], v[202:205], v[30:33]
	v_mfma_f32_16x16x32_f16 v[26:29], v[148:151], v[202:205], v[26:29]
	v_mfma_f32_16x16x32_f16 v[14:17], v[140:143], v[210:213], v[14:17]
	v_mfma_f32_16x16x32_f16 v[10:13], v[148:151], v[210:213], v[10:13]
	v_mfma_f32_16x16x32_f16 v[62:65], v[144:147], v[190:193], v[62:65]
	v_mfma_f32_16x16x32_f16 v[58:61], v[182:185], v[190:193], v[58:61]
	v_mfma_f32_16x16x32_f16 v[46:49], v[144:147], v[198:201], v[46:49]
	v_mfma_f32_16x16x32_f16 v[42:45], v[182:185], v[198:201], v[42:45]
	v_mfma_f32_16x16x32_f16 v[30:33], v[144:147], v[206:209], v[30:33]
	v_mfma_f32_16x16x32_f16 v[26:29], v[182:185], v[206:209], v[26:29]
	v_mfma_f32_16x16x32_f16 v[14:17], v[144:147], v[228:231], v[14:17]
	v_mfma_f32_16x16x32_f16 v[10:13], v[182:185], v[228:231], v[10:13]
	s_setprio 0
	s_barrier
; #define PG8_STAGE(bufoff, gbase, voff) do { _Pragma("unroll") for (int _i = 0; _i < 2; ++_i) \
;         __builtin_amdgcn_global_load_lds((const unsigned*)((const char*)(gbase) + (voff)[_i]), (LAS unsigned*)(lds + (bufoff) + ldsw + _i * 8192), 16, 0, 0); } while (0)
; #define PG8_LDA(dst, b, h) do { _Pragma("unroll") for (int m = 0; m < 4; ++m) _Pragma("unroll") for (int k = 0; k < 2; ++k) dst[m][k] = *(const LAS h16x8*)(lds + PG8_SA(b, h) + aoff + m * 2048 + k * 1024); } while (0)
; #define PG8_LDB(dst, b, h) do { _Pragma("unroll") for (int n = 0; n < 2; ++n) _Pragma("unroll") for (int k = 0; k < 2; ++k) dst[n][k] = *(const LAS h16x8*)(lds + PG8_SB(b, h) + boff + n * 2048 + k * 1024); } while (0)
; #define PG8_MMA(ai, bj, At, Bt) do { __builtin_amdgcn_s_setprio(1); _Pragma("unroll") for (int m = 0; m < 4; ++m) _Pragma("unroll") for (int n = 0; n < 2; ++n) _Pragma("unroll") for (int k = 0; k < 2; ++k) \
;         acc[ai][bj][m][n] = __builtin_amdgcn_mfma_f32_16x16x32_f16(Bt[n][k], At[m][k], acc[ai][bj][m][n], 0, 0, 0); __builtin_amdgcn_s_setprio(0); } while (0)
; #define PG8_WAIT_V(n) asm volatile("s_waitcnt vmcnt(" #n ")" ::: "memory")
; #define PG8_WAIT_L(n) asm volatile("s_waitcnt lgkmcnt(" #n ")" ::: "memory")
; #define PG8_BAR __builtin_amdgcn_s_barrier()
; #define PG8_SCHED __builtin_amdgcn_sched_barrier(0)
; template <class Epi>
; __device__ __forceinline__ void gemm_phase(LAS unsigned char* lds, const Gemm g, const StaticOrder& S, const Epi& E, const int wid_s) {
;     ...
;             PG8_STAGE(PG8_SB(0, 1), b2 + hstepB, voffB);
;             PG8_WAIT_V(6); PG8_BAR; PG8_MMA(1, 1, At, B1); PG8_BAR;
;             PG8_LDB(B0, 1, 0); PG8_SCHED; PG8_LDA(At, 1, 0); PG8_STAGE(PG8_SA(0, 1), a2 + hstepA, voffA);
;             PG8_WAIT_L(8); PG8_BAR; PG8_WAIT_L(0); PG8_MMA(0, 0, At, B0); PG8_BAR; PG8_SCHED;
;             PG8_LDB(B1, 1, 1); PG8_STAGE(PG8_SB(1, 0), b3, voffB);
;             PG8_BAR; PG8_WAIT_L(0); PG8_MMA(0, 1, At, B1); PG8_BAR;
;             PG8_LDA(At, 1, 1); PG8_STAGE(PG8_SA(1, 0), a3, voffA);
	s_add_u32 s24, s12, 0x40000
	s_addc_u32 s25, s13, 0
	s_add_i32 s26, s26, s51
	v_lshl_add_u64 v[140:141], s[24:25], 0, v[0:1]
	s_mov_b32 m0, s26
	s_nop 0
	global_load_lds_dwordx4 v[140:141], off
	v_lshl_add_u64 v[140:141], s[24:25], 0, v[130:131]
	s_add_i32 m0, s26, 0x2000
	s_nop 0
	global_load_lds_dwordx4 v[140:141], off
	s_waitcnt vmcnt(6)
	s_barrier
	s_setprio 1
	s_cmp_eq_u32 s66, 11
	s_cbranch_scc1 .Lpad_oddin_3
	v_mfma_f32_16x16x32_f16 v[54:57], v[232:235], v[186:189], v[54:57]
	v_mfma_f32_16x16x32_f16 v[50:53], v[240:243], v[186:189], v[50:53]
	v_mfma_f32_16x16x32_f16 v[38:41], v[232:235], v[194:197], v[38:41]
	v_mfma_f32_16x16x32_f16 v[34:37], v[240:243], v[194:197], v[34:37]
	v_mfma_f32_16x16x32_f16 v[22:25], v[232:235], v[202:205], v[22:25]
	v_mfma_f32_16x16x32_f16 v[18:21], v[240:243], v[202:205], v[18:21]
	v_mfma_f32_16x16x32_f16 v[6:9], v[232:235], v[210:213], v[6:9]
	v_mfma_f32_16x16x32_f16 v[2:5], v[240:243], v[210:213], v[2:5]
	v_mfma_f32_16x16x32_f16 v[54:57], v[236:239], v[190:193], v[54:57]
	v_mfma_f32_16x16x32_f16 v[50:53], v[244:247], v[190:193], v[50:53]
	v_mfma_f32_16x16x32_f16 v[38:41], v[236:239], v[198:201], v[38:41]
	v_mfma_f32_16x16x32_f16 v[34:37], v[244:247], v[198:201], v[34:37]
	v_mfma_f32_16x16x32_f16 v[22:25], v[236:239], v[206:209], v[22:25]
	v_mfma_f32_16x16x32_f16 v[18:21], v[244:247], v[206:209], v[18:21]
	v_mfma_f32_16x16x32_f16 v[6:9], v[236:239], v[228:231], v[6:9]
	v_mfma_f32_16x16x32_f16 v[2:5], v[244:247], v[228:231], v[2:5]
.Lpad_oddin_3:
	s_setprio 0
	s_add_i32 s24, 0, 0x18000
	v_add_u32_e32 v182, s24, v161
	s_barrier
	ds_read_b128 v[140:143], v182
	ds_read_b128 v[144:147], v182 offset:1024
	ds_read_b128 v[148:151], v182 offset:2048
	ds_read_b128 v[182:185], v182 offset:3072
	s_add_u32 s14, s14, 0x40000
	s_addc_u32 s15, s15, 0
	s_mov_b32 m0, s54
	v_lshl_add_u64 v[232:233], s[14:15], 0, v[134:135]
	ds_read_b128 v[186:189], v181 offset:32768
	ds_read_b128 v[190:193], v181 offset:33792
	ds_read_b128 v[194:197], v181 offset:34816
	ds_read_b128 v[198:201], v181 offset:35840
	ds_read_b128 v[202:205], v181 offset:36864
	ds_read_b128 v[206:209], v181 offset:37888
	ds_read_b128 v[210:213], v181 offset:38912
	ds_read_b128 v[228:231], v181 offset:39936
	global_load_lds_dwordx4 v[232:233], off
	v_lshl_add_u64 v[232:233], s[14:15], 0, v[132:133]
	s_mov_b32 m0, s55
	s_nop 0
	global_load_lds_dwordx4 v[232:233], off
	s_waitcnt lgkmcnt(8)
	s_barrier
	s_waitcnt lgkmcnt(0)
	s_setprio 1
	s_waitcnt lgkmcnt(0)
	v_mfma_f32_16x16x32_f16 v[126:129], v[140:143], v[186:189], v[126:129]
	v_mfma_f32_16x16x32_f16 v[122:125], v[148:151], v[186:189], v[122:125]
	v_mfma_f32_16x16x32_f16 v[110:113], v[140:143], v[194:197], v[110:113]
	v_mfma_f32_16x16x32_f16 v[106:109], v[148:151], v[194:197], v[106:109]
	v_mfma_f32_16x16x32_f16 v[94:97], v[140:143], v[202:205], v[94:97]
	v_mfma_f32_16x16x32_f16 v[90:93], v[148:151], v[202:205], v[90:93]
	v_mfma_f32_16x16x32_f16 v[78:81], v[140:143], v[210:213], v[78:81]
	v_mfma_f32_16x16x32_f16 v[74:77], v[148:151], v[210:213], v[74:77]
	v_mfma_f32_16x16x32_f16 v[126:129], v[144:147], v[190:193], v[126:129]
	v_mfma_f32_16x16x32_f16 v[122:125], v[182:185], v[190:193], v[122:125]
	v_mfma_f32_16x16x32_f16 v[110:113], v[144:147], v[198:201], v[110:113]
	v_mfma_f32_16x16x32_f16 v[106:109], v[182:185], v[198:201], v[106:109]
	v_mfma_f32_16x16x32_f16 v[94:97], v[144:147], v[206:209], v[94:97]
	v_mfma_f32_16x16x32_f16 v[90:93], v[182:185], v[206:209], v[90:93]
	v_mfma_f32_16x16x32_f16 v[78:81], v[144:147], v[228:231], v[78:81]
	v_mfma_f32_16x16x32_f16 v[74:77], v[182:185], v[228:231], v[74:77]
	s_setprio 0
	s_barrier
	s_add_i32 s14, 0, 0x1c000
	s_add_i32 s15, s24, s51
	v_add_u32_e32 v227, s14, v161
	v_lshl_add_u64 v[152:153], v[152:153], 0, s[74:75]
	s_mov_b32 m0, s15
	s_cmp_eq_u32 s66, 11
	s_cbranch_scc1 .Lpad_oddin_2
	ds_read_b128 v[232:235], v227
	ds_read_b128 v[236:239], v227 offset:1024
	ds_read_b128 v[240:243], v227 offset:2048
	ds_read_b128 v[244:247], v227 offset:3072
; #define PG8_STAGE(bufoff, gbase, voff) do { _Pragma("unroll") for (int _i = 0; _i < 2; ++_i) \
;         __builtin_amdgcn_global_load_lds((const unsigned*)((const char*)(gbase) + (voff)[_i]), (LAS unsigned*)(lds + (bufoff) + ldsw + _i * 8192), 16, 0, 0); } while (0)
; #define PG8_LDA(dst, b, h) do { _Pragma("unroll") for (int m = 0; m < 4; ++m) _Pragma("unroll") for (int k = 0; k < 2; ++k) dst[m][k] = *(const LAS h16x8*)(lds + PG8_SA(b, h) + aoff + m * 2048 + k * 1024); } while (0)
; #define PG8_LDB(dst, b, h) do { _Pragma("unroll") for (int n = 0; n < 2; ++n) _Pragma("unroll") for (int k = 0; k < 2; ++k) dst[n][k] = *(const LAS h16x8*)(lds + PG8_SB(b, h) + boff + n * 2048 + k * 1024); } while (0)
; #define PG8_MMA(ai, bj, At, Bt) do { __builtin_amdgcn_s_setprio(1); _Pragma("unroll") for (int m = 0; m < 4; ++m) _Pragma("unroll") for (int n = 0; n < 2; ++n) _Pragma("unroll") for (int k = 0; k < 2; ++k) \
;         acc[ai][bj][m][n] = __builtin_amdgcn_mfma_f32_16x16x32_f16(Bt[n][k], At[m][k], acc[ai][bj][m][n], 0, 0, 0); __builtin_amdgcn_s_setprio(0); } while (0)
; #define PG8_WAIT_V(n) asm volatile("s_waitcnt vmcnt(" #n ")" ::: "memory")
; #define PG8_WAIT_L(n) asm volatile("s_waitcnt lgkmcnt(" #n ")" ::: "memory")
; #define PG8_BAR __builtin_amdgcn_s_barrier()
; #define PG8_SCHED __builtin_amdgcn_sched_barrier(0)
; template <class Epi>
; __device__ __forceinline__ void gemm_phase(LAS unsigned char* lds, const Gemm g, const StaticOrder& S, const Epi& E, const int wid_s) {
;     ...
;             PG8_LDB(B1, 1, 1); PG8_STAGE(PG8_SB(1, 0), b3, voffB);
;             PG8_BAR; PG8_WAIT_L(0); PG8_MMA(0, 1, At, B1); PG8_BAR;
;             PG8_LDA(At, 1, 1); PG8_STAGE(PG8_SA(1, 0), a3, voffA);
;             PG8_BAR; PG8_WAIT_L(0); PG8_MMA(1, 0, At, B0); PG8_BAR; PG8_SCHED;
;             PG8_STAGE(PG8_SB(1, 1), b3 + hstepB, voffB);
;             PG8_WAIT_V(6); PG8_BAR; PG8_MMA(1, 1, At, B1); PG8_BAR;
.Lpad_oddin_2:
	global_load_lds_dwordx4 v[152:153], off
	v_lshl_add_u64 v[152:153], v[214:215], 0, s[74:75]
	s_add_i32 m0, s15, 0x2000
	s_nop 0
	global_load_lds_dwordx4 v[152:153], off
	s_barrier
	s_waitcnt lgkmcnt(0)
	s_setprio 1
	s_waitcnt lgkmcnt(0)
	s_cmp_eq_u32 s66, 11
	s_cbranch_scc1 .Lpad_oddin_1
	v_mfma_f32_16x16x32_f16 v[118:121], v[232:235], v[186:189], v[118:121]
	v_mfma_f32_16x16x32_f16 v[114:117], v[240:243], v[186:189], v[114:117]
	v_mfma_f32_16x16x32_f16 v[102:105], v[232:235], v[194:197], v[102:105]
	v_mfma_f32_16x16x32_f16 v[98:101], v[240:243], v[194:197], v[98:101]
	v_mfma_f32_16x16x32_f16 v[86:89], v[232:235], v[202:205], v[86:89]
	v_mfma_f32_16x16x32_f16 v[82:85], v[240:243], v[202:205], v[82:85]
	v_mfma_f32_16x16x32_f16 v[70:73], v[232:235], v[210:213], v[70:73]
	v_mfma_f32_16x16x32_f16 v[66:69], v[240:243], v[210:213], v[66:69]
	v_mfma_f32_16x16x32_f16 v[118:121], v[236:239], v[190:193], v[118:121]
	v_mfma_f32_16x16x32_f16 v[114:117], v[244:247], v[190:193], v[114:117]
	v_mfma_f32_16x16x32_f16 v[102:105], v[236:239], v[198:201], v[102:105]
	v_mfma_f32_16x16x32_f16 v[98:101], v[244:247], v[198:201], v[98:101]
	v_mfma_f32_16x16x32_f16 v[86:89], v[236:239], v[206:209], v[86:89]
	v_mfma_f32_16x16x32_f16 v[82:85], v[244:247], v[206:209], v[82:85]
	v_mfma_f32_16x16x32_f16 v[70:73], v[236:239], v[228:231], v[70:73]
	v_mfma_f32_16x16x32_f16 v[66:69], v[244:247], v[228:231], v[66:69]
.Lpad_oddin_1:
	s_setprio 0
	s_mov_b32 m0, s62
	v_lshl_add_u64 v[152:153], v[248:249], 0, s[74:75]
	s_barrier
	ds_read_b128 v[186:189], v181 offset:49152
	ds_read_b128 v[190:193], v181 offset:50176
	ds_read_b128 v[194:197], v181 offset:51200
	ds_read_b128 v[198:201], v181 offset:52224
	ds_read_b128 v[202:205], v181 offset:53248
	ds_read_b128 v[206:209], v181 offset:54272
	ds_read_b128 v[210:213], v181 offset:55296
	ds_read_b128 v[228:231], v181 offset:56320
	global_load_lds_dwordx4 v[152:153], off
	v_lshl_add_u64 v[152:153], v[250:251], 0, s[74:75]
	s_mov_b32 m0, s63
	s_nop 0
	global_load_lds_dwordx4 v[152:153], off
	s_barrier
	s_waitcnt lgkmcnt(0)
	s_setprio 1
	s_waitcnt lgkmcnt(0)
	v_mfma_f32_16x16x32_f16 v[62:65], v[140:143], v[186:189], v[62:65]
	v_mfma_f32_16x16x32_f16 v[58:61], v[148:151], v[186:189], v[58:61]
	v_mfma_f32_16x16x32_f16 v[46:49], v[140:143], v[194:197], v[46:49]
	v_mfma_f32_16x16x32_f16 v[42:45], v[148:151], v[194:197], v[42:45]
	v_mfma_f32_16x16x32_f16 v[30:33], v[140:143], v[202:205], v[30:33]
	v_mfma_f32_16x16x32_f16 v[26:29], v[148:151], v[202:205], v[26:29]
	v_mfma_f32_16x16x32_f16 v[14:17], v[140:143], v[210:213], v[14:17]
	v_mfma_f32_16x16x32_f16 v[10:13], v[148:151], v[210:213], v[10:13]
	v_mfma_f32_16x16x32_f16 v[62:65], v[144:147], v[190:193], v[62:65]
	v_mfma_f32_16x16x32_f16 v[58:61], v[182:185], v[190:193], v[58:61]
	v_mfma_f32_16x16x32_f16 v[46:49], v[144:147], v[198:201], v[46:49]
	v_mfma_f32_16x16x32_f16 v[42:45], v[182:185], v[198:201], v[42:45]
	v_mfma_f32_16x16x32_f16 v[30:33], v[144:147], v[206:209], v[30:33]
	v_mfma_f32_16x16x32_f16 v[26:29], v[182:185], v[206:209], v[26:29]
	v_mfma_f32_16x16x32_f16 v[14:17], v[144:147], v[228:231], v[14:17]
	v_mfma_f32_16x16x32_f16 v[10:13], v[182:185], v[228:231], v[10:13]
	s_setprio 0
	s_barrier
	s_add_u32 s12, s12, 0x40080
	s_addc_u32 s13, s13, 0
	s_add_i32 s14, s14, s51
	v_lshl_add_u64 v[140:141], s[12:13], 0, v[0:1]
	s_mov_b32 m0, s14
	s_nop 0
	global_load_lds_dwordx4 v[140:141], off
	v_lshl_add_u64 v[140:141], s[12:13], 0, v[130:131]
	s_add_i32 m0, s14, 0x2000
	s_nop 0
	global_load_lds_dwordx4 v[140:141], off
	s_waitcnt vmcnt(6)
	s_barrier
	s_setprio 1
	s_cmp_eq_u32 s66, 11
	s_cbranch_scc1 .Lpad_oddin_0
	v_mfma_f32_16x16x32_f16 v[54:57], v[232:235], v[186:189], v[54:57]
	v_mfma_f32_16x16x32_f16 v[50:53], v[240:243], v[186:189], v[50:53]
	v_mfma_f32_16x16x32_f16 v[38:41], v[232:235], v[194:197], v[38:41]
	v_mfma_f32_16x16x32_f16 v[34:37], v[240:243], v[194:197], v[34:37]
	v_mfma_f32_16x16x32_f16 v[22:25], v[232:235], v[202:205], v[22:25]
	v_mfma_f32_16x16x32_f16 v[18:21], v[240:243], v[202:205], v[18:21]
	v_mfma_f32_16x16x32_f16 v[6:9], v[232:235], v[210:213], v[6:9]
	v_mfma_f32_16x16x32_f16 v[2:5], v[240:243], v[210:213], v[2:5]
	v_mfma_f32_16x16x32_f16 v[54:57], v[236:239], v[190:193], v[54:57]
	v_mfma_f32_16x16x32_f16 v[50:53], v[244:247], v[190:193], v[50:53]
	v_mfma_f32_16x16x32_f16 v[38:41], v[236:239], v[198:201], v[38:41]
	v_mfma_f32_16x16x32_f16 v[34:37], v[244:247], v[198:201], v[34:37]
	v_mfma_f32_16x16x32_f16 v[22:25], v[236:239], v[206:209], v[22:25]
	v_mfma_f32_16x16x32_f16 v[18:21], v[244:247], v[206:209], v[18:21]
	v_mfma_f32_16x16x32_f16 v[6:9], v[236:239], v[228:231], v[6:9]
	v_mfma_f32_16x16x32_f16 v[2:5], v[244:247], v[228:231], v[2:5]
.Lpad_oddin_0:
	s_setprio 0
	s_add_i32 s23, s23, 2
	s_add_u32 s4, s4, 0x100
	s_addc_u32 s5, s5, 0
	s_add_u32 s21, s21, 0x100
	s_addc_u32 s22, s22, 0
	s_cmp_gt_u32 s23, 13
	s_barrier
	s_cbranch_scc0 .LBB0_146
	s_cmpk_gt_u32 s46, 0xff
	s_cbranch_scc1 .Lalign_oddin_a
	s_barrier

; #define PG8_STAGE(bufoff, gbase, voff) do { _Pragma("unroll") for (int _i = 0; _i < 2; ++_i) \
;         __builtin_amdgcn_global_load_lds((const unsigned*)((const char*)(gbase) + (voff)[_i]), (LAS unsigned*)(lds + (bufoff) + ldsw + _i * 8192), 16, 0, 0); } while (0)
; #define PG8_LDA(dst, b, h) do { _Pragma("unroll") for (int m = 0; m < 4; ++m) _Pragma("unroll") for (int k = 0; k < 2; ++k) dst[m][k] = *(const LAS h16x8*)(lds + PG8_SA(b, h) + aoff + m * 2048 + k * 1024); } while (0)
; #define PG8_LDB(dst, b, h) do { _Pragma("unroll") for (int n = 0; n < 2; ++n) _Pragma("unroll") for (int k = 0; k < 2; ++k) dst[n][k] = *(const LAS h16x8*)(lds + PG8_SB(b, h) + boff + n * 2048 + k * 1024); } while (0)
; #define PG8_MMA(ai, bj, At, Bt) do { __builtin_amdgcn_s_setprio(1); _Pragma("unroll") for (int m = 0; m < 4; ++m) _Pragma("unroll") for (int n = 0; n < 2; ++n) _Pragma("unroll") for (int k = 0; k < 2; ++k) \
;         acc[ai][bj][m][n] = __builtin_amdgcn_mfma_f32_16x16x32_f16(Bt[n][k], At[m][k], acc[ai][bj][m][n], 0, 0, 0); __builtin_amdgcn_s_setprio(0); } while (0)
; #define PG8_WAIT_V(n) asm volatile("s_waitcnt vmcnt(" #n ")" ::: "memory")
; #define PG8_WAIT_L(n) asm volatile("s_waitcnt lgkmcnt(" #n ")" ::: "memory")
; #define PG8_BAR __builtin_amdgcn_s_barrier()
; #define PG8_SCHED __builtin_amdgcn_sched_barrier(0)
; template <class Epi>
; __device__ __forceinline__ void gemm_phase(LAS unsigned char* lds, const Gemm g, const StaticOrder& S, const Epi& E, const int wid_s) {
;     ...
;             PG8_LDB(B0, 0, 0); PG8_SCHED; PG8_LDA(At, 0, 0); PG8_STAGE(PG8_SA(1, 1), a1 + hstepA, voffA);
;             PG8_WAIT_L(8); PG8_BAR; PG8_WAIT_L(0); PG8_MMA(0, 0, At, B0); PG8_BAR; PG8_SCHED;
;             PG8_LDB(B1, 0, 1); PG8_STAGE(PG8_SB(0, 0), b2, voffB);
;             PG8_BAR; PG8_WAIT_L(0); PG8_MMA(0, 1, At, B1); PG8_BAR;
;             PG8_LDA(At, 0, 1); PG8_STAGE(PG8_SA(0, 0), a2, voffA);
;             PG8_BAR; PG8_WAIT_L(0); PG8_MMA(1, 0, At, B0); PG8_BAR; PG8_SCHED;
;             PG8_STAGE(PG8_SB(0, 1), b2 + hstepB, voffB);
;             PG8_WAIT_V(6); PG8_BAR; PG8_MMA(1, 1, At, B1); PG8_BAR;
.LBB0_861:
	s_add_u32 s10, s4, 0xfffc0080
	s_addc_u32 s11, s5, -1
	s_add_i32 s50, 0, 0x10000
	v_add_u32_e32 v152, s50, v155
	ds_read_b128 v[130:133], v152
	ds_read_b128 v[134:137], v152 offset:1024
	ds_read_b128 v[148:151], v152 offset:2048
	ds_read_b128 v[164:167], v152 offset:3072
	s_cmp_eq_u32 s49, 12
	s_cselect_b32 s13, s23, s11
	s_cselect_b32 s12, s45, s10
	s_cselect_b32 s11, s21, s48
	s_cselect_b32 s10, s46, s47
	v_lshl_add_u64 v[152:153], s[4:5], 0, v[144:145]
	s_add_i32 m0, s36, 0xc000
	ds_read_b128 v[168:171], v162
	ds_read_b128 v[172:175], v162 offset:1024
	ds_read_b128 v[176:179], v162 offset:2048
	ds_read_b128 v[180:183], v162 offset:3072
	ds_read_b128 v[184:187], v162 offset:4096
	ds_read_b128 v[188:191], v162 offset:5120
	ds_read_b128 v[192:195], v162 offset:6144
	ds_read_b128 v[196:199], v162 offset:7168
	global_load_lds_dwordx4 v[152:153], off
	v_lshl_add_u64 v[152:153], s[4:5], 0, v[146:147]
	s_add_i32 m0, s36, 0xe000
	s_nop 0
	global_load_lds_dwordx4 v[152:153], off
	s_waitcnt lgkmcnt(8)
	s_barrier
	s_waitcnt lgkmcnt(0)
	s_setprio 1
	s_waitcnt lgkmcnt(0)
	v_mfma_f32_16x16x32_f16 v[126:129], v[130:133], v[168:171], v[126:129]
	v_mfma_f32_16x16x32_f16 v[122:125], v[148:151], v[168:171], v[122:125]
	v_mfma_f32_16x16x32_f16 v[110:113], v[130:133], v[176:179], v[110:113]
	v_mfma_f32_16x16x32_f16 v[106:109], v[148:151], v[176:179], v[106:109]
	v_mfma_f32_16x16x32_f16 v[94:97], v[130:133], v[184:187], v[94:97]
	v_mfma_f32_16x16x32_f16 v[90:93], v[148:151], v[184:187], v[90:93]
	v_mfma_f32_16x16x32_f16 v[78:81], v[130:133], v[192:195], v[78:81]
	v_mfma_f32_16x16x32_f16 v[74:77], v[148:151], v[192:195], v[74:77]
	v_mfma_f32_16x16x32_f16 v[126:129], v[134:137], v[172:175], v[126:129]
	v_mfma_f32_16x16x32_f16 v[122:125], v[164:167], v[172:175], v[122:125]
	v_mfma_f32_16x16x32_f16 v[110:113], v[134:137], v[180:183], v[110:113]
	v_mfma_f32_16x16x32_f16 v[106:109], v[164:167], v[180:183], v[106:109]
	v_mfma_f32_16x16x32_f16 v[94:97], v[134:137], v[188:191], v[94:97]
	v_mfma_f32_16x16x32_f16 v[90:93], v[164:167], v[188:191], v[90:93]
	v_mfma_f32_16x16x32_f16 v[78:81], v[134:137], v[196:199], v[78:81]
	v_mfma_f32_16x16x32_f16 v[74:77], v[164:167], v[196:199], v[74:77]
	s_setprio 0
	s_barrier
	s_add_i32 s52, 0, 0x14000
	v_add_u32_e32 v152, s52, v155
	s_add_i32 s50, s50, s35
	s_cmp_eq_u32 s43, 12
	s_cbranch_scc1 .Lpad_evin_5
	ds_read_b128 v[200:203], v152
	ds_read_b128 v[204:207], v152 offset:1024
	ds_read_b128 v[208:211], v152 offset:2048
	ds_read_b128 v[212:215], v152 offset:3072
.Lpad_evin_5:
	v_lshl_add_u64 v[152:153], s[10:11], 0, v[0:1]
	s_mov_b32 m0, s50
	v_lshl_add_u64 v[228:229], s[10:11], 0, v[138:139]
	global_load_lds_dwordx4 v[152:153], off
	s_add_i32 m0, s50, 0x2000
	s_nop 0
	global_load_lds_dwordx4 v[228:229], off
	s_barrier
	s_waitcnt lgkmcnt(0)
	s_setprio 1
	s_waitcnt lgkmcnt(0)
	s_cmp_eq_u32 s43, 12
	s_cbranch_scc1 .Lpad_evin_4
	v_mfma_f32_16x16x32_f16 v[118:121], v[200:203], v[168:171], v[118:121]
	v_mfma_f32_16x16x32_f16 v[114:117], v[208:211], v[168:171], v[114:117]
	v_mfma_f32_16x16x32_f16 v[102:105], v[200:203], v[176:179], v[102:105]
	v_mfma_f32_16x16x32_f16 v[98:101], v[208:211], v[176:179], v[98:101]
	v_mfma_f32_16x16x32_f16 v[86:89], v[200:203], v[184:187], v[86:89]
	v_mfma_f32_16x16x32_f16 v[82:85], v[208:211], v[184:187], v[82:85]
	v_mfma_f32_16x16x32_f16 v[70:73], v[200:203], v[192:195], v[70:73]
	v_mfma_f32_16x16x32_f16 v[66:69], v[208:211], v[192:195], v[66:69]
	v_mfma_f32_16x16x32_f16 v[118:121], v[204:207], v[172:175], v[118:121]
	v_mfma_f32_16x16x32_f16 v[114:117], v[212:215], v[172:175], v[114:117]
	v_mfma_f32_16x16x32_f16 v[102:105], v[204:207], v[180:183], v[102:105]
	v_mfma_f32_16x16x32_f16 v[98:101], v[212:215], v[180:183], v[98:101]
	v_mfma_f32_16x16x32_f16 v[86:89], v[204:207], v[188:191], v[86:89]
	v_mfma_f32_16x16x32_f16 v[82:85], v[212:215], v[188:191], v[82:85]
	v_mfma_f32_16x16x32_f16 v[70:73], v[204:207], v[196:199], v[70:73]
	v_mfma_f32_16x16x32_f16 v[66:69], v[212:215], v[196:199], v[66:69]
.Lpad_evin_4:
	s_setprio 0
	s_mov_b32 m0, s36
	v_lshl_add_u64 v[230:231], s[12:13], 0, v[142:143]
	s_barrier
	ds_read_b128 v[168:171], v162 offset:16384
	ds_read_b128 v[172:175], v162 offset:17408
	ds_read_b128 v[176:179], v162 offset:18432
	ds_read_b128 v[180:183], v162 offset:19456
	ds_read_b128 v[184:187], v162 offset:20480
	ds_read_b128 v[188:191], v162 offset:21504
	ds_read_b128 v[192:195], v162 offset:22528
	ds_read_b128 v[196:199], v162 offset:23552
	global_load_lds_dwordx4 v[230:231], off
	v_lshl_add_u64 v[232:233], s[12:13], 0, v[140:141]
	s_mov_b32 m0, s37
	s_nop 0
	global_load_lds_dwordx4 v[232:233], off
	s_barrier
	s_waitcnt lgkmcnt(0)
	s_setprio 1
	s_waitcnt lgkmcnt(0)
	v_mfma_f32_16x16x32_f16 v[62:65], v[130:133], v[168:171], v[62:65]
	v_mfma_f32_16x16x32_f16 v[58:61], v[148:151], v[168:171], v[58:61]
	v_mfma_f32_16x16x32_f16 v[46:49], v[130:133], v[176:179], v[46:49]
	v_mfma_f32_16x16x32_f16 v[42:45], v[148:151], v[176:179], v[42:45]
	v_mfma_f32_16x16x32_f16 v[30:33], v[130:133], v[184:187], v[30:33]
	v_mfma_f32_16x16x32_f16 v[26:29], v[148:151], v[184:187], v[26:29]
	v_mfma_f32_16x16x32_f16 v[14:17], v[130:133], v[192:195], v[14:17]
	v_mfma_f32_16x16x32_f16 v[10:13], v[148:151], v[192:195], v[10:13]
	v_mfma_f32_16x16x32_f16 v[62:65], v[134:137], v[172:175], v[62:65]
	v_mfma_f32_16x16x32_f16 v[58:61], v[164:167], v[172:175], v[58:61]
	v_mfma_f32_16x16x32_f16 v[46:49], v[134:137], v[180:183], v[46:49]
	v_mfma_f32_16x16x32_f16 v[42:45], v[164:167], v[180:183], v[42:45]
	v_mfma_f32_16x16x32_f16 v[30:33], v[134:137], v[188:191], v[30:33]
	v_mfma_f32_16x16x32_f16 v[26:29], v[164:167], v[188:191], v[26:29]
	v_mfma_f32_16x16x32_f16 v[14:17], v[134:137], v[196:199], v[14:17]
	v_mfma_f32_16x16x32_f16 v[10:13], v[164:167], v[196:199], v[10:13]
	s_setprio 0
	s_barrier
; #define PG8_STAGE(bufoff, gbase, voff) do { _Pragma("unroll") for (int _i = 0; _i < 2; ++_i) \
;         __builtin_amdgcn_global_load_lds((const unsigned*)((const char*)(gbase) + (voff)[_i]), (LAS unsigned*)(lds + (bufoff) + ldsw + _i * 8192), 16, 0, 0); } while (0)
; #define PG8_LDA(dst, b, h) do { _Pragma("unroll") for (int m = 0; m < 4; ++m) _Pragma("unroll") for (int k = 0; k < 2; ++k) dst[m][k] = *(const LAS h16x8*)(lds + PG8_SA(b, h) + aoff + m * 2048 + k * 1024); } while (0)
; #define PG8_LDB(dst, b, h) do { _Pragma("unroll") for (int n = 0; n < 2; ++n) _Pragma("unroll") for (int k = 0; k < 2; ++k) dst[n][k] = *(const LAS h16x8*)(lds + PG8_SB(b, h) + boff + n * 2048 + k * 1024); } while (0)
; #define PG8_MMA(ai, bj, At, Bt) do { __builtin_amdgcn_s_setprio(1); _Pragma("unroll") for (int m = 0; m < 4; ++m) _Pragma("unroll") for (int n = 0; n < 2; ++n) _Pragma("unroll") for (int k = 0; k < 2; ++k) \
;         acc[ai][bj][m][n] = __builtin_amdgcn_mfma_f32_16x16x32_f16(Bt[n][k], At[m][k], acc[ai][bj][m][n], 0, 0, 0); __builtin_amdgcn_s_setprio(0); } while (0)
; #define PG8_WAIT_V(n) asm volatile("s_waitcnt vmcnt(" #n ")" ::: "memory")
; #define PG8_WAIT_L(n) asm volatile("s_waitcnt lgkmcnt(" #n ")" ::: "memory")
; #define PG8_BAR __builtin_amdgcn_s_barrier()
; #define PG8_SCHED __builtin_amdgcn_sched_barrier(0)
; template <class Epi>
; __device__ __forceinline__ void gemm_phase(LAS unsigned char* lds, const Gemm g, const StaticOrder& S, const Epi& E, const int wid_s) {
;     ...
;             PG8_STAGE(PG8_SB(0, 1), b2 + hstepB, voffB);
;             PG8_WAIT_V(6); PG8_BAR; PG8_MMA(1, 1, At, B1); PG8_BAR;
;             PG8_LDB(B0, 1, 0); PG8_SCHED; PG8_LDA(At, 1, 0); PG8_STAGE(PG8_SA(0, 1), a2 + hstepA, voffA);
;             PG8_WAIT_L(8); PG8_BAR; PG8_WAIT_L(0); PG8_MMA(0, 0, At, B0); PG8_BAR; PG8_SCHED;
;             PG8_LDB(B1, 1, 1); PG8_STAGE(PG8_SB(1, 0), b3, voffB);
;             PG8_BAR; PG8_WAIT_L(0); PG8_MMA(0, 1, At, B1); PG8_BAR;
;             PG8_LDA(At, 1, 1); PG8_STAGE(PG8_SA(1, 0), a3, voffA);
	s_add_u32 s50, s10, 0x40000
	s_addc_u32 s51, s11, 0
	s_add_i32 s52, s52, s35
	v_lshl_add_u64 v[130:131], s[50:51], 0, v[0:1]
	s_mov_b32 m0, s52
	s_nop 0
	global_load_lds_dwordx4 v[130:131], off
	v_lshl_add_u64 v[130:131], s[50:51], 0, v[138:139]
	s_add_i32 m0, s52, 0x2000
	s_nop 0
	global_load_lds_dwordx4 v[130:131], off
	s_waitcnt vmcnt(6)
	s_barrier
	s_setprio 1
	s_cmp_eq_u32 s43, 12
	s_cbranch_scc1 .Lpad_evin_3
	v_mfma_f32_16x16x32_f16 v[54:57], v[200:203], v[168:171], v[54:57]
	v_mfma_f32_16x16x32_f16 v[50:53], v[208:211], v[168:171], v[50:53]
	v_mfma_f32_16x16x32_f16 v[38:41], v[200:203], v[176:179], v[38:41]
	v_mfma_f32_16x16x32_f16 v[34:37], v[208:211], v[176:179], v[34:37]
	v_mfma_f32_16x16x32_f16 v[22:25], v[200:203], v[184:187], v[22:25]
	v_mfma_f32_16x16x32_f16 v[18:21], v[208:211], v[184:187], v[18:21]
	v_mfma_f32_16x16x32_f16 v[6:9], v[200:203], v[192:195], v[6:9]
	v_mfma_f32_16x16x32_f16 v[2:5], v[208:211], v[192:195], v[2:5]
	v_mfma_f32_16x16x32_f16 v[54:57], v[204:207], v[172:175], v[54:57]
	v_mfma_f32_16x16x32_f16 v[50:53], v[212:215], v[172:175], v[50:53]
	v_mfma_f32_16x16x32_f16 v[38:41], v[204:207], v[180:183], v[38:41]
	v_mfma_f32_16x16x32_f16 v[34:37], v[212:215], v[180:183], v[34:37]
	v_mfma_f32_16x16x32_f16 v[22:25], v[204:207], v[188:191], v[22:25]
	v_mfma_f32_16x16x32_f16 v[18:21], v[212:215], v[188:191], v[18:21]
	v_mfma_f32_16x16x32_f16 v[6:9], v[204:207], v[196:199], v[6:9]
	v_mfma_f32_16x16x32_f16 v[2:5], v[212:215], v[196:199], v[2:5]
.Lpad_evin_3:
	s_setprio 0
	s_add_i32 s50, 0, 0x18000
	v_add_u32_e32 v163, s50, v155
	s_barrier
	ds_read_b128 v[130:133], v163
	ds_read_b128 v[134:137], v163 offset:1024
	ds_read_b128 v[148:151], v163 offset:2048
	ds_read_b128 v[164:167], v163 offset:3072
	s_add_u32 s12, s12, 0x40000
	s_addc_u32 s13, s13, 0
	s_mov_b32 m0, s38
	v_lshl_add_u64 v[200:201], s[12:13], 0, v[142:143]
	ds_read_b128 v[168:171], v162 offset:32768
	ds_read_b128 v[172:175], v162 offset:33792
	ds_read_b128 v[176:179], v162 offset:34816
	ds_read_b128 v[180:183], v162 offset:35840
	ds_read_b128 v[184:187], v162 offset:36864
	ds_read_b128 v[188:191], v162 offset:37888
	ds_read_b128 v[192:195], v162 offset:38912
	ds_read_b128 v[196:199], v162 offset:39936
	global_load_lds_dwordx4 v[200:201], off
	v_lshl_add_u64 v[200:201], s[12:13], 0, v[140:141]
	s_mov_b32 m0, s39
	s_nop 0
	global_load_lds_dwordx4 v[200:201], off
	s_waitcnt lgkmcnt(8)
	s_barrier
	s_waitcnt lgkmcnt(0)
	s_setprio 1
	s_waitcnt lgkmcnt(0)
	v_mfma_f32_16x16x32_f16 v[126:129], v[130:133], v[168:171], v[126:129]
	v_mfma_f32_16x16x32_f16 v[122:125], v[148:151], v[168:171], v[122:125]
	v_mfma_f32_16x16x32_f16 v[110:113], v[130:133], v[176:179], v[110:113]
	v_mfma_f32_16x16x32_f16 v[106:109], v[148:151], v[176:179], v[106:109]
	v_mfma_f32_16x16x32_f16 v[94:97], v[130:133], v[184:187], v[94:97]
	v_mfma_f32_16x16x32_f16 v[90:93], v[148:151], v[184:187], v[90:93]
	v_mfma_f32_16x16x32_f16 v[78:81], v[130:133], v[192:195], v[78:81]
	v_mfma_f32_16x16x32_f16 v[74:77], v[148:151], v[192:195], v[74:77]
	v_mfma_f32_16x16x32_f16 v[126:129], v[134:137], v[172:175], v[126:129]
	v_mfma_f32_16x16x32_f16 v[122:125], v[164:167], v[172:175], v[122:125]
	v_mfma_f32_16x16x32_f16 v[110:113], v[134:137], v[180:183], v[110:113]
	v_mfma_f32_16x16x32_f16 v[106:109], v[164:167], v[180:183], v[106:109]
	v_mfma_f32_16x16x32_f16 v[94:97], v[134:137], v[188:191], v[94:97]
	v_mfma_f32_16x16x32_f16 v[90:93], v[164:167], v[188:191], v[90:93]
	v_mfma_f32_16x16x32_f16 v[78:81], v[134:137], v[196:199], v[78:81]
	v_mfma_f32_16x16x32_f16 v[74:77], v[164:167], v[196:199], v[74:77]
	s_setprio 0
	s_barrier
	s_add_i32 s12, 0, 0x1c000
	s_add_i32 s13, s50, s35
	v_add_u32_e32 v163, s12, v155
	v_lshl_add_u64 v[152:153], v[152:153], 0, s[74:75]
	s_mov_b32 m0, s13
	s_cmp_eq_u32 s43, 12
	s_cbranch_scc1 .Lpad_evin_2
	ds_read_b128 v[200:203], v163
	ds_read_b128 v[204:207], v163 offset:1024
	ds_read_b128 v[208:211], v163 offset:2048
	ds_read_b128 v[212:215], v163 offset:3072
; #define PG8_STAGE(bufoff, gbase, voff) do { _Pragma("unroll") for (int _i = 0; _i < 2; ++_i) \
;         __builtin_amdgcn_global_load_lds((const unsigned*)((const char*)(gbase) + (voff)[_i]), (LAS unsigned*)(lds + (bufoff) + ldsw + _i * 8192), 16, 0, 0); } while (0)
; #define PG8_LDA(dst, b, h) do { _Pragma("unroll") for (int m = 0; m < 4; ++m) _Pragma("unroll") for (int k = 0; k < 2; ++k) dst[m][k] = *(const LAS h16x8*)(lds + PG8_SA(b, h) + aoff + m * 2048 + k * 1024); } while (0)
; #define PG8_LDB(dst, b, h) do { _Pragma("unroll") for (int n = 0; n < 2; ++n) _Pragma("unroll") for (int k = 0; k < 2; ++k) dst[n][k] = *(const LAS h16x8*)(lds + PG8_SB(b, h) + boff + n * 2048 + k * 1024); } while (0)
; #define PG8_MMA(ai, bj, At, Bt) do { __builtin_amdgcn_s_setprio(1); _Pragma("unroll") for (int m = 0; m < 4; ++m) _Pragma("unroll") for (int n = 0; n < 2; ++n) _Pragma("unroll") for (int k = 0; k < 2; ++k) \
;         acc[ai][bj][m][n] = __builtin_amdgcn_mfma_f32_16x16x32_f16(Bt[n][k], At[m][k], acc[ai][bj][m][n], 0, 0, 0); __builtin_amdgcn_s_setprio(0); } while (0)
; #define PG8_WAIT_V(n) asm volatile("s_waitcnt vmcnt(" #n ")" ::: "memory")
; #define PG8_WAIT_L(n) asm volatile("s_waitcnt lgkmcnt(" #n ")" ::: "memory")
; #define PG8_BAR __builtin_amdgcn_s_barrier()
; #define PG8_SCHED __builtin_amdgcn_sched_barrier(0)
; template <class Epi>
; __device__ __forceinline__ void gemm_phase(LAS unsigned char* lds, const Gemm g, const StaticOrder& S, const Epi& E, const int wid_s) {
;     ...
;             PG8_LDB(B1, 1, 1); PG8_STAGE(PG8_SB(1, 0), b3, voffB);
;             PG8_BAR; PG8_WAIT_L(0); PG8_MMA(0, 1, At, B1); PG8_BAR;
;             PG8_LDA(At, 1, 1); PG8_STAGE(PG8_SA(1, 0), a3, voffA);
;             PG8_BAR; PG8_WAIT_L(0); PG8_MMA(1, 0, At, B0); PG8_BAR; PG8_SCHED;
;             PG8_STAGE(PG8_SB(1, 1), b3 + hstepB, voffB);
;             PG8_WAIT_V(6); PG8_BAR; PG8_MMA(1, 1, At, B1); PG8_BAR;
.Lpad_evin_2:
	global_load_lds_dwordx4 v[152:153], off
	v_lshl_add_u64 v[152:153], v[228:229], 0, s[74:75]
	s_add_i32 m0, s13, 0x2000
	s_nop 0
	global_load_lds_dwordx4 v[152:153], off
	s_barrier
	s_waitcnt lgkmcnt(0)
	s_setprio 1
	s_waitcnt lgkmcnt(0)
	s_cmp_eq_u32 s43, 12
	s_cbranch_scc1 .Lpad_evin_1
	v_mfma_f32_16x16x32_f16 v[118:121], v[200:203], v[168:171], v[118:121]
	v_mfma_f32_16x16x32_f16 v[114:117], v[208:211], v[168:171], v[114:117]
	v_mfma_f32_16x16x32_f16 v[102:105], v[200:203], v[176:179], v[102:105]
	v_mfma_f32_16x16x32_f16 v[98:101], v[208:211], v[176:179], v[98:101]
	v_mfma_f32_16x16x32_f16 v[86:89], v[200:203], v[184:187], v[86:89]
	v_mfma_f32_16x16x32_f16 v[82:85], v[208:211], v[184:187], v[82:85]
	v_mfma_f32_16x16x32_f16 v[70:73], v[200:203], v[192:195], v[70:73]
	v_mfma_f32_16x16x32_f16 v[66:69], v[208:211], v[192:195], v[66:69]
	v_mfma_f32_16x16x32_f16 v[118:121], v[204:207], v[172:175], v[118:121]
	v_mfma_f32_16x16x32_f16 v[114:117], v[212:215], v[172:175], v[114:117]
	v_mfma_f32_16x16x32_f16 v[102:105], v[204:207], v[180:183], v[102:105]
	v_mfma_f32_16x16x32_f16 v[98:101], v[212:215], v[180:183], v[98:101]
	v_mfma_f32_16x16x32_f16 v[86:89], v[204:207], v[188:191], v[86:89]
	v_mfma_f32_16x16x32_f16 v[82:85], v[212:215], v[188:191], v[82:85]
	v_mfma_f32_16x16x32_f16 v[70:73], v[204:207], v[196:199], v[70:73]
	v_mfma_f32_16x16x32_f16 v[66:69], v[212:215], v[196:199], v[66:69]
.Lpad_evin_1:
	s_setprio 0
	s_mov_b32 m0, s40
	v_lshl_add_u64 v[152:153], v[230:231], 0, s[74:75]
	s_barrier
	ds_read_b128 v[168:171], v162 offset:49152
	ds_read_b128 v[172:175], v162 offset:50176
	ds_read_b128 v[176:179], v162 offset:51200
	ds_read_b128 v[180:183], v162 offset:52224
	ds_read_b128 v[184:187], v162 offset:53248
	ds_read_b128 v[188:191], v162 offset:54272
	ds_read_b128 v[192:195], v162 offset:55296
	ds_read_b128 v[196:199], v162 offset:56320
	global_load_lds_dwordx4 v[152:153], off
	v_lshl_add_u64 v[152:153], v[232:233], 0, s[74:75]
	s_mov_b32 m0, s41
	s_nop 0
	global_load_lds_dwordx4 v[152:153], off
	s_barrier
	s_waitcnt lgkmcnt(0)
	s_setprio 1
	s_waitcnt lgkmcnt(0)
	v_mfma_f32_16x16x32_f16 v[62:65], v[130:133], v[168:171], v[62:65]
	v_mfma_f32_16x16x32_f16 v[58:61], v[148:151], v[168:171], v[58:61]
	v_mfma_f32_16x16x32_f16 v[46:49], v[130:133], v[176:179], v[46:49]
	v_mfma_f32_16x16x32_f16 v[42:45], v[148:151], v[176:179], v[42:45]
	v_mfma_f32_16x16x32_f16 v[30:33], v[130:133], v[184:187], v[30:33]
	v_mfma_f32_16x16x32_f16 v[26:29], v[148:151], v[184:187], v[26:29]
	v_mfma_f32_16x16x32_f16 v[14:17], v[130:133], v[192:195], v[14:17]
	v_mfma_f32_16x16x32_f16 v[10:13], v[148:151], v[192:195], v[10:13]
	v_mfma_f32_16x16x32_f16 v[62:65], v[134:137], v[172:175], v[62:65]
	v_mfma_f32_16x16x32_f16 v[58:61], v[164:167], v[172:175], v[58:61]
	v_mfma_f32_16x16x32_f16 v[46:49], v[134:137], v[180:183], v[46:49]
	v_mfma_f32_16x16x32_f16 v[42:45], v[164:167], v[180:183], v[42:45]
	v_mfma_f32_16x16x32_f16 v[30:33], v[134:137], v[188:191], v[30:33]
	v_mfma_f32_16x16x32_f16 v[26:29], v[164:167], v[188:191], v[26:29]
	v_mfma_f32_16x16x32_f16 v[14:17], v[134:137], v[196:199], v[14:17]
	v_mfma_f32_16x16x32_f16 v[10:13], v[164:167], v[196:199], v[10:13]
	s_setprio 0
	s_barrier
	s_add_u32 s10, s10, 0x40080
	s_addc_u32 s11, s11, 0
	s_add_i32 s12, s12, s35
	v_lshl_add_u64 v[130:131], s[10:11], 0, v[0:1]
	s_mov_b32 m0, s12
	s_nop 0
	global_load_lds_dwordx4 v[130:131], off
	v_lshl_add_u64 v[130:131], s[10:11], 0, v[138:139]
	s_add_i32 m0, s12, 0x2000
	s_nop 0
	global_load_lds_dwordx4 v[130:131], off
	s_waitcnt vmcnt(6)
	s_barrier
	s_setprio 1
	s_cmp_eq_u32 s43, 12
	s_cbranch_scc1 .Lpad_evin_0
	v_mfma_f32_16x16x32_f16 v[54:57], v[200:203], v[168:171], v[54:57]
	v_mfma_f32_16x16x32_f16 v[50:53], v[208:211], v[168:171], v[50:53]
	v_mfma_f32_16x16x32_f16 v[38:41], v[200:203], v[176:179], v[38:41]
	v_mfma_f32_16x16x32_f16 v[34:37], v[208:211], v[176:179], v[34:37]
	v_mfma_f32_16x16x32_f16 v[22:25], v[200:203], v[184:187], v[22:25]
	v_mfma_f32_16x16x32_f16 v[18:21], v[208:211], v[184:187], v[18:21]
	v_mfma_f32_16x16x32_f16 v[6:9], v[200:203], v[192:195], v[6:9]
	v_mfma_f32_16x16x32_f16 v[2:5], v[208:211], v[192:195], v[2:5]
	v_mfma_f32_16x16x32_f16 v[54:57], v[204:207], v[172:175], v[54:57]
	v_mfma_f32_16x16x32_f16 v[50:53], v[212:215], v[172:175], v[50:53]
	v_mfma_f32_16x16x32_f16 v[38:41], v[204:207], v[180:183], v[38:41]
	v_mfma_f32_16x16x32_f16 v[34:37], v[212:215], v[180:183], v[34:37]
	v_mfma_f32_16x16x32_f16 v[22:25], v[204:207], v[188:191], v[22:25]
	v_mfma_f32_16x16x32_f16 v[18:21], v[212:215], v[188:191], v[18:21]
	v_mfma_f32_16x16x32_f16 v[6:9], v[204:207], v[196:199], v[6:9]
	v_mfma_f32_16x16x32_f16 v[2:5], v[212:215], v[196:199], v[2:5]
.Lpad_evin_0:
	s_setprio 0
	s_add_i32 s49, s49, 2
	s_add_u32 s4, s4, 0x100
	s_addc_u32 s5, s5, 0
	s_add_u32 s47, s47, 0x100
	s_addc_u32 s48, s48, 0
	s_cmp_gt_u32 s49, 13
	s_barrier
	s_cbranch_scc0 .LBB0_861
	s_cmpk_gt_u32 s28, 0xff
	s_cbranch_scc1 .Lalign_evin_a
	s_barrier
